# v34 + banded attention: 8 Q-fragment loads in flight at unit start (were 8 serial load-wait-store chains) and Q/K LDS swizzle widened to 4 row bits
# baseline (speedup 1.0000x reference)
; template <int MODE> ...
;     ...
;   if constexpr (MODE == 1) { const int cq = qc0 + (wid >> 1); jlo = (cq - 8 > 0 ? cq - 8 : 0) - kc0; jhi = cq - kc0; }
;   if constexpr (MODE == 2) { jhi = qc0 + (wid >> 1) - kc0; }
;   if constexpr (MODE == 1) { if (tid < 257) tb[tid] = bias_g[tid] * 1.4426950408889634f; }
;   float m_reg = -1e30f, l_reg = 0; f32x16 o[4] = {}; bf16x8 qr[8];
;   char* Q2s = (MODE == 1) ? lds + OFF_Q1 + wid * 8192 : lds + OFF_Q2 + wid * 4096;
;   char* QHs = lds + OFF_QH + wid * 4096; char* Q3s = lds + OFF_Q3 + wid * 1024 + lane * 16;
;   const bf16_t* Qw = Qb + (long)(wid * QBLK + r32) * ldq + hi * 8;
;   if constexpr (MODE == 1) {
; #pragma unroll
;     for (int d0 = 0; d0 < 8; ++d0) *reinterpret_cast<bf16x8*>(Q2s + KSWZ(r32, (d0 * 16 + hi * 8) * 2)) = *reinterpret_cast<const bf16x8*>(Qw + d0 * 16);
;     asm volatile("s_waitcnt lgkmcnt(0)" ::: "memory");
;   } else if constexpr (MODE == 2) {
; #pragma unroll
;     for (int d0 = 0; d0 < 3; ++d0) qr[d0] = *reinterpret_cast<const bf16x8*>(Qw + d0 * 16);
;     *reinterpret_cast<bf16x8*>(Q3s) = *reinterpret_cast<const bf16x8*>(Qw + 3 * 16);
; #pragma unroll
;     for (int d0 = 4; d0 < 8; ++d0) *reinterpret_cast<bf16x8*>(QHs + K2SWZ(r32, ((d0 - 4) * 16 + hi * 8) * 2)) = *reinterpret_cast<const bf16x8*>(Qw + d0 * 16);
;     asm volatile("s_waitcnt lgkmcnt(0)" ::: "memory");
;   } else {
; #pragma unroll
;     for (int d0 = 0; d0 < 8; ++d0) qr[d0] = *reinterpret_cast<const bf16x8*>(Qw + d0 * 16);
;   }
;   if constexpr (MODE == 2) { const bf16_t* Q2w = Q2b + (long)(wid * QBLK + r32) * ldq2 + hi * 8;
; #pragma unroll
;     for (int d0 = 0; d0 < 4; ++d0) *reinterpret_cast<bf16x8*>(Q2s + K2SWZ(r32, (d0 * 16 + hi * 8) * 2)) = *reinterpret_cast<const bf16x8*>(Q2w + d0 * 16);
;     ...
;             const int it = ui - 512, xcd = it & 7, slot = it >> 3, bh = xcd * 4 + (slot >> 4), qb = slot & 15, b = bh >> 3, h = bh & 7;
;             const int qc0 = 4 * qb, kc0 = qc0 > 8 ? qc0 - 8 : 0;
;             const size_t qrow = (size_t)b * SEQ + 256 * qb, krow = (size_t)b * SEQ + 64 * kc0;
;     ...
;             att::attn_unit<1>(lds, PROJ + qrow * INP + h * 128, nullptr, PROJ + krow * INP + 1024 + h * 128, PROJ + krow * INP + 2048 + h * 128, nullptr,
;                               OB + qrow * DM + h * 128, INP, 0, INP, DM, qc0 + 4 - kc0, qc0, kc0, (const float*)a.in[5] + ((size_t)l * 8 + h) * 257);
.LBB0_210:
	s_or_b64 exec, exec, s[4:5]
	s_bfe_u32 s3, s54, 0x40003
	s_lshl_b32 s16, s3, 2
	s_lshr_b32 s24, s2, 3
	s_add_i32 s2, s16, -8
	s_cmp_gt_u32 s3, 2
	s_cselect_b32 s19, s2, 0
	s_lshl_b64 s[6:7], s[24:25], 12
	s_lshl_b32 s2, s3, 8
	s_lshl_b32 s17, s19, 6
	s_or_b32 s4, s6, s2
	s_ashr_i32 s2, s17, 31
	s_add_u32 s3, s6, s17
	s_mul_hi_u32 s6, s4, 0x2400
	s_mul_i32 s8, s7, 0x2400
	s_addc_u32 s2, s7, s2
	s_mul_i32 s5, s4, 0x2400
	s_add_i32 s6, s6, s8
	s_add_u32 s5, s76, s5
	s_addc_u32 s6, s77, s6
	s_lshl_b32 s8, s15, 8
	s_add_u32 s22, s5, s8
	s_mulk_i32 s2, 0x2400
	s_mul_hi_u32 s5, s3, 0x2400
	s_addc_u32 s23, s6, 0
	s_add_i32 s5, s5, s2
	s_mulk_i32 s3, 0x2400
	s_add_u32 s2, s76, s3
	s_addc_u32 s3, s77, s5
	s_add_u32 s12, s2, s8
	s_addc_u32 s13, s3, 0
	s_add_u32 s8, s12, 0x800
	s_addc_u32 s9, s13, 0
	s_add_u32 s10, s12, 0x1000
	s_addc_u32 s11, s13, 0
	s_ashr_i32 s2, s18, 7
	s_add_i32 s2, s2, s16
	s_ashr_i32 s6, s18, 6
	s_max_i32 s3, s2, 8
	v_and_b32_e32 v183, 31, v80
	s_sub_i32 s5, s3, s19
	s_lshl_b32 s3, s6, 13
	s_lshl_b32 s6, s6, 5
	v_bfe_u32 v182, v80, 5, 1
	v_or_b32_e32 v1, s6, v183
	v_mov_b64_e32 v[2:3], s[22:23]
	s_movk_i32 s22, 0x2400
	v_mad_i64_i32 v[2:3], s[22:23], v1, s22, v[2:3]
	v_lshlrev_b32_e32 v174, 4, v182
	v_lshl_add_u64 v[6:7], v[2:3], 0, v[174:175]
	global_load_dwordx4 v[2:5], v[6:7], off
	s_add_i32 s3, s3, 0
	s_add_i32 s3, s3, 0x11000
	v_lshlrev_b32_e32 v185, 8, v183
	v_add_u32_e32 v8, s3, v185
	v_bitop3_b32 v9, v182, v80, 15 bitop3:0x78
	v_lshl_add_u32 v9, v9, 4, v8
	v_lshlrev_b32_e32 v1, 4, v80
	v_and_b32_e32 v1, 0xf0, v1
	v_or_b32_e32 v192, 32, v174
	v_or_b32_e32 v191, 64, v174
	v_or_b32_e32 v190, 0x60, v174
	v_or_b32_e32 v189, 0x80, v174
	v_or_b32_e32 v188, 0xa0, v174
	v_or_b32_e32 v187, 0xc0, v174
	v_or_b32_e32 v186, 0xe0, v174
	v_ashrrev_i32_e32 v81, 4, v80
	v_add_u32_e32 v20, 32, v81
	s_movk_i32 s22, 0x1200
	v_mad_i64_i32 v[84:85], s[22:23], v81, s22, 0
	s_mov_b64 s[22:23], 0x48000
	s_sub_i32 s2, s2, s19
	s_cmp_lt_i32 s5, 9
	global_load_dwordx4 v[24:27], v[6:7], off offset:32
	global_load_dwordx4 v[28:31], v[6:7], off offset:64
	global_load_dwordx4 v[32:35], v[6:7], off offset:96
	global_load_dwordx4 v[36:39], v[6:7], off offset:128
	global_load_dwordx4 v[40:43], v[6:7], off offset:160
	global_load_dwordx4 v[44:47], v[6:7], off offset:192
	global_load_dwordx4 v[48:51], v[6:7], off offset:224
	s_waitcnt vmcnt(0)
	ds_write_b128 v9, v[2:5]
	v_xad_u32 v9, v192, v1, v8
	ds_write_b128 v9, v[24:27]
	v_xad_u32 v9, v191, v1, v8
	ds_write_b128 v9, v[28:31]
	v_xad_u32 v9, v190, v1, v8
	ds_write_b128 v9, v[32:35]
	v_xad_u32 v9, v189, v1, v8
	ds_write_b128 v9, v[36:39]
	v_xad_u32 v9, v188, v1, v8
	ds_write_b128 v9, v[40:43]
	v_xad_u32 v9, v187, v1, v8
	v_xad_u32 v1, v186, v1, v8
	ds_write_b128 v9, v[44:47]
	ds_write_b128 v1, v[48:51]
	v_and_b32_e32 v2, 0xfffff0, v81
	v_lshlrev_b32_e32 v3, 1, v81
	v_lshlrev_b32_e32 v1, 3, v80
	v_and_or_b32 v2, v3, 8, v2
	v_and_b32_e32 v82, 0x78, v1
	v_lshrrev_b32_e32 v3, 1, v81
	v_lshrrev_b32_e32 v2, 1, v2
	v_bfe_u32 v1, v1, 5, 2
	v_and_b32_e32 v4, 3, v81
	v_or_b32_e32 v2, v2, v1
	v_and_or_b32 v3, v3, 4, v4
	v_lshlrev_b32_e32 v18, 1, v82
	v_lshlrev_b32_e32 v2, 9, v2
	v_lshlrev_b32_e32 v3, 6, v3
	v_and_b32_e32 v4, 48, v18
	v_or3_b32 v19, v2, v3, v4
	v_and_b32_e32 v2, 0xfffff0, v20
	v_lshlrev_b32_e32 v5, 1, v20
	v_and_or_b32 v2, v5, 8, v2
	v_lshrrev_b32_e32 v2, 1, v2
	v_or_b32_e32 v1, v2, v1
	v_lshlrev_b32_e32 v1, 9, v1
	v_or3_b32 v1, v1, v3, v4
	v_or_b32_e32 v2, v84, v82
	v_mov_b32_e32 v3, v85
	v_lshlrev_b64 v[10:11], 1, v[2:3]
	s_waitcnt lgkmcnt(0)
	v_lshl_add_u64 v[2:3], s[10:11], 0, v[10:11]
	global_load_dwordx4 v[2:5], v[2:3], off
	v_lshl_add_u64 v[14:15], v[10:11], 0, s[22:23]
	v_lshl_add_u64 v[6:7], s[10:11], 0, v[14:15]
	v_lshl_add_u64 v[10:11], s[12:13], 0, v[10:11]
	v_lshl_add_u64 v[14:15], s[8:9], 0, v[14:15]
	global_load_dwordx4 v[6:9], v[6:7], off
	v_add_u32_e32 v203, 0, v19
	global_load_dwordx4 v[10:13], v[10:11], off offset:2048
	v_add_u32_e32 v204, 0, v1
	global_load_dwordx4 v[14:17], v[14:15], off
	s_waitcnt vmcnt(0)
	v_lshlrev_b32_e32 v1, 8, v81
	s_cselect_b64 s[12:13], -1, 0
	s_cmp_gt_i32 s2, -1
	s_cselect_b64 s[22:23], -1, 0
	s_and_b64 s[12:13], s[12:13], s[22:23]
	s_andn2_b64 vcc, exec, s[12:13]
	s_waitcnt vmcnt(3)
	ds_write_b128 v203, v[2:5]
	v_and_b32_e32 v2, 0xf0, v80
	v_bitop3_b32 v1, v18, v1, v2 bitop3:0xde
	v_add_u32_e32 v205, 0, v1
	v_lshlrev_b32_e32 v1, 8, v20
	v_bitop3_b32 v1, v18, v1, v2 bitop3:0xde
	v_add_u32_e32 v206, 0, v1
	v_cndmask_b32_e64 v1, 0, 1, s[12:13]
	v_cmp_ne_u32_e64 s[36:37], 1, v1
	v_lshlrev_b32_e32 v1, 4, v183
	v_and_b32_e32 v207, 0xf0, v1
	s_waitcnt vmcnt(2)
	ds_write_b128 v204, v[6:9]
	s_waitcnt vmcnt(1)
	ds_write_b128 v205, v[10:13] offset:32768
	s_waitcnt vmcnt(0)
	ds_write_b128 v206, v[14:17] offset:32768
	s_waitcnt lgkmcnt(0)
	s_barrier
; template <int MODE>
; __device__ __forceinline__ void qkt(f32x16& p0, f32x16& p1, const char* Ks, const char* K2s, const bf16x8* qr, const char* Q2s, const char* QHs, const char* Q3s, int r32, int hi, bool valid) {
;   if constexpr (MODE == 1) {
;     if (!valid) {
; #pragma unroll
;       for (int r = 0; r < 16; ++r) { p0[r] = -INFINITY; p1[r] = -INFINITY; }
;       return; }
;     p0 = f32x16{}; p1 = f32x16{};
; #pragma unroll
;     for (int d0 = 0; d0 < 8; ++d0) { const int cb = (d0 * 16 + hi * 8) * 2;
;       bf16x8 b0 = *reinterpret_cast<const bf16x8*>(Ks + KSWZ(r32, cb));
;       bf16x8 b1 = *reinterpret_cast<const bf16x8*>(Ks + KSWZ(32 + r32, cb));
;       bf16x8 qf = *reinterpret_cast<const bf16x8*>(Q2s + KSWZ(r32, cb));
;       p0 = __builtin_amdgcn_mfma_f32_32x32x16_bf16(b0, qf, p0, 0, 0, 0);
;       p1 = __builtin_amdgcn_mfma_f32_32x32x16_bf16(b1, qf, p1, 0, 0, 0); }
	s_cbranch_vccnz .LBB0_212
	v_bitop3_b32 v1, v174, v185, v207 bitop3:0xde
	v_add_u32_e32 v10, 0, v1
	ds_read_b128 v[2:5], v10 offset:32768
	v_add_u32_e32 v1, s3, v1
	ds_read_b128 v[6:9], v1
	v_bitop3_b32 v1, v192, v185, v207 bitop3:0xde
	s_waitcnt lgkmcnt(0)
	v_mfma_f32_32x32x16_bf16 v[32:47], v[2:5], v[6:9], 0
	ds_read_b128 v[2:5], v10 offset:40960
	v_add_u32_e32 v10, 0, v1
	v_add_u32_e32 v1, s3, v1
	s_waitcnt lgkmcnt(0)
	v_mfma_f32_32x32x16_bf16 v[16:31], v[2:5], v[6:9], 0
	ds_read_b128 v[2:5], v10 offset:32768
	ds_read_b128 v[6:9], v1
	v_bitop3_b32 v1, v191, v185, v207 bitop3:0xde
	s_waitcnt lgkmcnt(0)
	v_mfma_f32_32x32x16_bf16 v[32:47], v[2:5], v[6:9], v[32:47]
	ds_read_b128 v[2:5], v10 offset:40960
	v_add_u32_e32 v10, 0, v1
	v_add_u32_e32 v1, s3, v1
	s_waitcnt lgkmcnt(0)
	v_mfma_f32_32x32x16_bf16 v[16:31], v[2:5], v[6:9], v[16:31]
	ds_read_b128 v[2:5], v10 offset:32768
	ds_read_b128 v[6:9], v1
	v_bitop3_b32 v1, v190, v185, v207 bitop3:0xde
	s_waitcnt lgkmcnt(0)
	v_mfma_f32_32x32x16_bf16 v[32:47], v[2:5], v[6:9], v[32:47]
	ds_read_b128 v[2:5], v10 offset:40960
	v_add_u32_e32 v10, 0, v1
	v_add_u32_e32 v1, s3, v1
	s_waitcnt lgkmcnt(0)
	v_mfma_f32_32x32x16_bf16 v[16:31], v[2:5], v[6:9], v[16:31]
	ds_read_b128 v[2:5], v10 offset:32768
	ds_read_b128 v[6:9], v1
	v_bitop3_b32 v1, v189, v185, v207 bitop3:0xde
	s_waitcnt lgkmcnt(0)
	v_mfma_f32_32x32x16_bf16 v[32:47], v[2:5], v[6:9], v[32:47]
	ds_read_b128 v[2:5], v10 offset:40960
	v_add_u32_e32 v10, 0, v1
	v_add_u32_e32 v1, s3, v1
	s_waitcnt lgkmcnt(0)
	v_mfma_f32_32x32x16_bf16 v[16:31], v[2:5], v[6:9], v[16:31]
	ds_read_b128 v[2:5], v10 offset:32768
	ds_read_b128 v[6:9], v1
	v_bitop3_b32 v1, v188, v185, v207 bitop3:0xde
	s_waitcnt lgkmcnt(0)
	v_mfma_f32_32x32x16_bf16 v[32:47], v[2:5], v[6:9], v[32:47]
	ds_read_b128 v[2:5], v10 offset:40960
	v_add_u32_e32 v10, 0, v1
	v_add_u32_e32 v1, s3, v1
	s_waitcnt lgkmcnt(0)
	v_mfma_f32_32x32x16_bf16 v[16:31], v[2:5], v[6:9], v[16:31]
	ds_read_b128 v[2:5], v10 offset:32768
	ds_read_b128 v[6:9], v1
	v_bitop3_b32 v1, v187, v185, v207 bitop3:0xde
	s_waitcnt lgkmcnt(0)
	v_mfma_f32_32x32x16_bf16 v[32:47], v[2:5], v[6:9], v[32:47]
	ds_read_b128 v[2:5], v10 offset:40960
	v_add_u32_e32 v10, 0, v1
	v_add_u32_e32 v1, s3, v1
	s_waitcnt lgkmcnt(0)
	v_mfma_f32_32x32x16_bf16 v[16:31], v[2:5], v[6:9], v[16:31]
	ds_read_b128 v[2:5], v10 offset:32768
	ds_read_b128 v[6:9], v1
	v_bitop3_b32 v1, v186, v185, v207 bitop3:0xde
	s_waitcnt lgkmcnt(0)
	v_mfma_f32_32x32x16_bf16 v[32:47], v[2:5], v[6:9], v[32:47]
	ds_read_b128 v[2:5], v10 offset:40960
	v_add_u32_e32 v10, 0, v1
	v_add_u32_e32 v1, s3, v1
	s_waitcnt lgkmcnt(0)
	v_mfma_f32_32x32x16_bf16 v[16:31], v[2:5], v[6:9], v[16:31]
	ds_read_b128 v[2:5], v10 offset:32768
	ds_read_b128 v[6:9], v1
	s_waitcnt lgkmcnt(0)
	v_mfma_f32_32x32x16_bf16 v[32:47], v[2:5], v[6:9], v[32:47]
	ds_read_b128 v[2:5], v10 offset:40960
	s_waitcnt lgkmcnt(0)
	v_mfma_f32_32x32x16_bf16 v[16:31], v[2:5], v[6:9], v[16:31]
	s_branch .LBB0_213
